# batch-local P3 order with per-XCC rotation of the weight-tile order (XCCs no longer fetch the same tiles at once) + SEAM3 XCC-local wait
# speedup vs baseline: 1.0065x; 1.0065x over previous
; template <class Epi, class Sched, bool ALIGN_EPI = false, bool SP2 = false>
; __device__ __forceinline__ void gemm_phase(PG8_LAS unsigned char* lds, const Gemm g, const Sched& S, const Epi& E) {
;     const int tid = threadIdx.x, wid = __builtin_amdgcn_readfirstlane(tid >> 6), lane = tid & 63, wr = wid >> 2, wc = wid & 3, fr = lane & 15, fq = lane >> 4;
;     const int K = g.K, nt = K / BK;
;     unsigned voffA[2], voffB[2];
; #pragma unroll
;     for (int i = 0; i < 2; ++i) { int R, C; stage_rc(tid * 16 + i * 8192, R, C); const int Rb = Epi::PERM ? ((R & ~31) + perm32(R & 31)) : R;
;         voffA[i] = (unsigned)(R * K + C) * 2u; voffB[i] = (unsigned)(Rb * K + C) * 2u; }
;     const size_t kstep = (size_t)(BK * 2);
;     const size_t hstep = (size_t)HALF * K * 2;
;     const size_t tstep = 2 * hstep;
;     const unsigned ldsw = (unsigned)wid * 1024u;
;     const int aoff = lds_byte(wr * 64 + fr, fq * 8), boff = lds_byte(wc * 32 + fr, fq * 8);
;     ...
;     Unit cur, nxt; int ui = 0;
;     if (!S.next(0, cur)) return;
;     f32x4 acc[2][2][4][2];
; #pragma unroll
;     for (int a = 0; a < 2; ++a)
; #pragma unroll
;         for (int b = 0; b < 2; ++b)
; #pragma unroll
;             for (int m = 0; m < 4; ++m)
; #pragma unroll
;                 for (int n = 0; n < 2; ++n) acc[a][b][m][n] = (f32x4){0.f, 0.f, 0.f, 0.f};
;     bf16x8 At[4][2], B0[2][2], B1[2][2];
;     const char* cA = (const char*)g.A + (size_t)cur.pm * tstep; const char* cB = (const char*)g.Bt + (size_t)cur.pn * tstep;
;     S.a_ready(cur);
;     if constexpr (SP2) {
;         PG8_STAGE(PG8_SB(0, 0), cB, voffB); PG8_STAGE(PG8_SB(0, 1), cB + hstep, voffB); PG8_STAGE(PG8_SA(0, 0), cA, voffA); PG8_STAGE(PG8_SA(0, 1), cA + hstep, voffA);
;         if (wr == 1) PG8_BAR;
;         PG8_WAIT_V(2); PG8_BAR;
;         PG8_STAGE(PG8_SB(1, 0), cB + kstep, voffB); PG8_STAGE(PG8_SA(1, 0), cA + kstep, voffA); PG8_STAGE(PG8_SB(1, 1), cB + hstep + kstep, voffB);
;         PG8_WAIT_V(6); PG8_BAR;
;     } else {
;         PG8_STAGE(PG8_SB(0, 0), cB, voffB); PG8_STAGE(PG8_SA(0, 0), cA, voffA); PG8_STAGE(PG8_SB(0, 1), cB + hstep, voffB); PG8_STAGE(PG8_SA(0, 1), cA + hstep, voffA);
;         if (wr == 1) PG8_BAR;
;         PG8_WAIT_V(4); PG8_BAR;
;         PG8_STAGE(PG8_SB(1, 0), cB + kstep, voffB); PG8_STAGE(PG8_SA(1, 0), cA + kstep, voffA); PG8_STAGE(PG8_SB(1, 1), cB + hstep + kstep, voffB);
.LBB0_317:
	s_add_u32 s98, s78, 0x1f03800
	s_addc_u32 s99, s79, 0
	s_mov_b32 s100, 0
	s_cmp_lt_i32 s82, 4
	s_cselect_b64 s[4:5], -1, 0
	s_and_b64 s[4:5], s[4:5], s[0:1]
	s_andn2_b64 vcc, exec, s[4:5]
	s_cbranch_vccnz .LBB0_350
	s_cmpk_gt_i32 s2, 0x2ff
	v_readfirstlane_b32 s1, v188
	s_cbranch_scc1 .LBB0_350
	s_waitcnt vmcnt(0)
	v_lshrrev_b32_e32 v0, 5, v188
	v_lshrrev_b32_e32 v2, 1, v188
	v_and_b32_e32 v0, 4, v0
	v_bfe_u32 v1, v188, 2, 2
	v_and_b32_e32 v2, 24, v2
	v_or3_b32 v0, v0, v1, v2
	v_lshlrev_b32_e32 v1, 4, v188
	v_add_u32_e32 v8, 0x2000, v1
	v_lshrrev_b32_e32 v2, 7, v8
	s_movk_i32 s0, 0xe0
	v_and_b32_e32 v4, 32, v188
	v_and_or_b32 v3, v2, s0, v0
	v_bitop3_b32 v9, v1, v4, 48 bitop3:0x6c
	v_and_b32_e32 v10, 64, v188
	v_bfe_u32 v11, v188, 2, 4
	s_movk_i32 s0, 0xf0
	v_or_b32_e32 v1, v9, v10
	v_and_or_b32 v2, v2, s0, v11
	s_add_u32 s48, s78, 0x2000000
	v_lshl_or_b32 v130, v2, 11, v1
	v_lshrrev_b32_e32 v2, 3, v188
	s_movk_i32 s0, 0x60
	s_addc_u32 s49, s79, 0
	v_and_or_b32 v0, v2, s0, v0
	s_movk_i32 s0, 0x70
	s_ashr_i32 s51, s2, 31
	v_lshl_or_b32 v132, v0, 11, v1
	v_and_or_b32 v0, v2, s0, v11
	s_lshr_b32 s0, s51, 29
	s_add_i32 s0, s2, s0
	s_lshr_b32 s9, s1, 6
	s_ashr_i32 s6, s0, 3
	s_and_b32 s0, s0, -8
	s_lshr_b32 s8, s1, 8
	s_lshl_b32 s50, s9, 10
	s_sub_i32 s0, s2, s0
	s_cmp_lt_i32 s0, 0
	s_movk_i32 s52, 0x61
	s_cselect_b32 s7, s52, 0x60
	s_mul_i32 s0, s0, s7
	s_add_i32 s0, s0, s6
	s_ashr_i32 s6, s0, 31
	s_lshr_b32 s6, s6, 25
	s_add_i32 s6, s0, s6
	s_ashr_i32 s7, s6, 7
	s_and_b32 s6, s6, 0xffffff80
	s_sub_i32 s6, s0, s6
	s_bfe_i32 s0, s6, 0x80000
	s_bfe_u32 s0, s0, 0x3000c
	s_add_i32 s10, s6, s0
	s_bfe_i32 s0, s10, 0x80000
	s_and_b32 s10, s10, 0xf8
	s_sub_i32 s6, s6, s10
	s_lshl_b32 s7, s7, 3
	s_sext_i32_i8 s6, s6
	s_add_i32 s7, s7, s6
	s_mul_hi_i32 s6, s7, 0x2aaaaaab
	s_lshr_b32 s10, s6, 31
	s_add_i32 s6, s6, s10
	s_lshl_b32 s10, s6, 3
	s_mul_i32 s6, s6, 6
	s_sext_i32_i16 s0, s0
	s_sub_i32 s6, s7, s6
	s_lshr_b32 s0, s0, 3
	s_add_i32 s40, s10, s6
	s_lshr_b32 s6, s2, 3
	s_and_b32 s10, s2, 7
	s_mul_i32 s10, s10, 12
	s_add_i32 s6, s6, s10
	s_sub_i32 s10, s6, 0x60
	s_cmp_ge_i32 s10, 0
	s_cselect_b32 s6, s10, s6
	s_mul_i32 s0, s6, 43
	s_lshr_b32 s0, s0, 8
	s_mul_i32 s10, s0, 6
	s_sub_i32 s6, s6, s10
	s_and_b32 s10, s2, 7
	s_lshl_b32 s10, s10, 3
	s_add_i32 s40, s10, s6
	s_ashr_i32 s41, s40, 31
	s_bfe_i64 s[10:11], s[0:1], 0x100000
	s_lshl_b64 s[6:7], s[40:41], 19
	s_lshl_b64 s[10:11], s[10:11], 19
	s_add_u32 s44, s78, s10
	s_addc_u32 s45, s79, s11
	s_add_i32 s53, s50, 0
	s_add_i32 m0, s53, 0x10000
	v_lshl_or_b32 v128, v3, 11, v1
	global_load_lds_dwordx4 v132, s[44:45]
	s_add_i32 m0, s53, 0x12000
	s_add_u32 s10, s44, 0x40000
	global_load_lds_dwordx4 v128, s[44:45]
	s_addc_u32 s11, s45, 0
	s_add_i32 m0, s53, 0x14000
	v_lshl_or_b32 v134, v0, 11, v1
	global_load_lds_dwordx4 v132, s[10:11]
	s_add_i32 m0, s53, 0x16000
	s_add_u32 s42, s48, s6
	s_addc_u32 s43, s49, s7
	s_waitcnt lgkmcnt(0)
	s_add_i32 s58, s53, 0x2000
	global_load_lds_dwordx4 v128, s[10:11]
	s_mov_b32 m0, s53
	s_add_u32 s6, s42, 0x40000
	global_load_lds_dwordx4 v134, s[42:43]
	s_mov_b32 m0, s58
	s_addc_u32 s7, s43, 0
	s_add_i32 s59, s53, 0x4000
	global_load_lds_dwordx4 v130, s[42:43]
	s_mov_b32 m0, s59
	s_add_i32 s60, s53, 0x6000
	global_load_lds_dwordx4 v134, s[6:7]
	s_mov_b32 m0, s60
	v_mov_b32_e32 v137, 0
	global_load_lds_dwordx4 v130, s[6:7]
	v_mov_b32_e32 v133, v137
	v_mov_b32_e32 v129, v137
	v_mov_b32_e32 v135, v137
	v_mov_b32_e32 v131, v137
	s_cmp_eq_u32 s8, 1
	s_movk_i32 s61, 0x2000
	s_mov_b32 s62, 0
	v_lshl_add_u64 v[6:7], s[44:45], 0, v[132:133]
	v_lshl_add_u64 v[2:3], s[44:45], 0, v[128:129]
	v_lshl_add_u64 v[0:1], s[42:43], 0, v[134:135]
	s_cselect_b64 s[6:7], -1, 0
	s_cmp_lg_u32 s8, 1
	v_lshl_add_u64 v[4:5], s[42:43], 0, v[130:131]
	s_cbranch_scc1 .LBB0_321
	s_barrier

;     __device__ __forceinline__ bool next(int i, Unit& u) const { const unsigned c = (i < 4) ? ((list >> (8 * i)) & 0xffu) : 0xffu; if (c == 0xffu) return false; u.pm = pm0 + (int)(c & 7u); u.pn = (int)(c >> 3); return true; }
;     __device__ __forceinline__ bool next(int i, Unit& u) const { if (!base.next(i, u)) return false; u.pm = (u.pm / 6) * 8 + (u.pm % 6); return true; }
;     __host__ __device__ bool next(int i, Unit& u) const {
;         const long L = (long)i * G + c; if (L >= nwg) return false;
;         int wgid = (int)L; { const int q = nwg / NXCD, r = nwg % NXCD, xcd = wgid % NXCD, off = wgid / NXCD; wgid = (xcd < r ? xcd * (q + 1) : r * (q + 1) + (xcd - r) * q) + off; }
;         const int nig = WGM * nN, gid = wgid / nig, fm = gid * WGM, gsz = (nM - fm) < WGM ? (nM - fm) : WGM;
;         u.pm = fm + ((wgid % nig) % gsz); u.pn = (wgid % nig) / gsz; return true;
;     }
; template <class Epi, class Sched, bool ALIGN_EPI = false, bool SP2 = false>
; __device__ __forceinline__ void gemm_phase(PG8_LAS unsigned char* lds, const Gemm g, const Sched& S, const Epi& E) {
;     ...
;         const bool has_next = S.next(ui + 1, nxt);
;         const char* nA = has_next ? (const char*)g.A + (size_t)nxt.pm * tstep : cA; const char* nB = has_next ? (const char*)g.Bt + (size_t)nxt.pn * tstep : cB;
.LBB0_324:
	s_add_i32 s62, s62, 1
	s_mul_i32 s0, s62, s70
	s_mul_hi_u32 s1, s62, s71
	s_add_i32 s1, s1, s0
	s_mul_i32 s0, s62, s71
	s_add_u32 s36, s0, s2
	s_addc_u32 s37, s1, s51
	v_cmp_gt_i64_e32 vcc, s[36:37], v[150:151]
	v_cmp_lt_i64_e64 s[0:1], s[36:37], v[148:149]
	s_cbranch_vccnz .LBB0_326
	s_ashr_i32 s30, s36, 31
	s_lshr_b32 s30, s30, 29
	s_add_i32 s30, s36, s30
	s_ashr_i32 s31, s30, 3
	s_and_b32 s30, s30, -8
	s_sub_i32 s30, s36, s30
	s_cmp_lt_i32 s30, 0
	s_cselect_b32 s34, s52, 0x60
	s_mul_i32 s30, s30, s34
	s_add_i32 s30, s30, s31
	s_ashr_i32 s31, s30, 31
	s_lshr_b32 s31, s31, 25
	s_add_i32 s31, s30, s31
	s_ashr_i32 s34, s31, 7
	s_lshl_b32 s34, s34, 3
	s_sub_i32 s35, 48, s34
	s_min_i32 s35, s35, 8
	s_abs_i32 s36, s35
	v_cvt_f32_u32_e32 v0, s36
	s_sub_i32 s38, 0, s36
	s_and_b32 s31, s31, 0xffffff80
	s_sub_i32 s31, s30, s31
	v_rcp_iflag_f32_e32 v0, v0
	s_abs_i32 s30, s31
	s_xor_b32 s37, s31, s35
	s_ashr_i32 s37, s37, 31
	v_mul_f32_e32 v0, 0x4f7ffffe, v0
	v_cvt_u32_f32_e32 v0, v0
	s_nop 0
	v_readfirstlane_b32 s39, v0
	s_mul_i32 s38, s38, s39
	s_mul_hi_u32 s38, s39, s38
	s_add_i32 s39, s39, s38
	s_mul_hi_u32 s38, s30, s39
	s_mul_i32 s39, s38, s36
	s_sub_i32 s30, s30, s39
	s_add_i32 s41, s38, 1
	s_sub_i32 s39, s30, s36
	s_cmp_ge_u32 s30, s36
	s_cselect_b32 s38, s41, s38
	s_cselect_b32 s30, s39, s30
	s_add_i32 s39, s38, 1
	s_cmp_ge_u32 s30, s36
	s_cselect_b32 s30, s39, s38
	s_xor_b32 s30, s30, s37
	s_sub_i32 s30, s30, s37
	s_mul_i32 s35, s30, s35
	s_sub_i32 s31, s31, s35
	s_add_i32 s34, s34, s31
	s_mul_hi_i32 s31, s34, 0x2aaaaaab
	s_lshr_b32 s35, s31, 31
	s_add_i32 s31, s31, s35
	s_lshl_b32 s35, s31, 3
	s_mul_i32 s31, s31, 6
	s_sub_i32 s31, s34, s31
	s_add_i32 s34, s35, s31
	s_lshl_b32 s31, s62, 5
	s_lshr_b32 s35, s2, 3
	s_add_i32 s31, s31, s35
	s_and_b32 s35, s2, 7
	s_mul_i32 s35, s35, 12
	s_add_i32 s31, s31, s35
	s_sub_i32 s35, s31, 0x60
	s_cmp_ge_i32 s35, 0
	s_cselect_b32 s31, s35, s31
	s_mul_i32 s30, s31, 43
	s_lshr_b32 s30, s30, 8
	s_mul_i32 s35, s30, 6
	s_sub_i32 s31, s31, s35
	s_and_b32 s35, s2, 7
	s_lshl_b32 s35, s35, 3
	s_add_i32 s34, s35, s31
